# grid barrier (in-loop instances, hand-written leader protocol): workgroups that are not the XCD's last arriver issue their agent-scope invalidate on arrival, before polling for the release, instead of
# speedup vs baseline: 1.0217x; 1.0097x over previous
.Lgb258_local:
	buffer_inv sc1
	s_waitcnt vmcnt(0)
	s_add_u32 s14, s6, 0x6400
	v_mov_b32_e32 v3, s14
	s_mov_b32 s16, 0x10000
	global_load_dword v6, v3, s[46:47] sc1
	s_sleep 4
	global_load_dword v7, v3, s[46:47] sc1
	s_sleep 4
	global_load_dword v8, v3, s[46:47] sc1
	s_sleep 4

.Lgb258l_out:
	s_waitcnt vmcnt(0)
	s_waitcnt vmcnt(0)
